# grid-barrier poll backoff s_sleep 3 (was 2)
# speedup vs baseline: 1.0036x; 1.0036x over previous
.LBB0_100:
	s_sleep 3
	global_load_dword v16, v17, s[34:35] sc1
	s_waitcnt vmcnt(0)
	v_cmp_gt_u32_e32 vcc, s59, v16
	s_cbranch_vccnz .LBB0_100

.LBB0_1750:
	s_sleep 3
	global_load_dword v0, v17, s[6:7] sc1
	s_waitcnt vmcnt(0)
	v_cmp_gt_u32_e32 vcc, s36, v0
	s_cbranch_vccnz .LBB0_1750
	s_getpc_b64 s[98:99]
